# v11 plus HGRN2 scan sum-of-squares 8-lane reduction via DPP instead of three ds_bpermute round trips per chunk
# speedup vs baseline: 1.0015x; 1.0015x over previous
; #define LAS __attribute__((address_space(3)))
; __device__ __forceinline__ void scan_item(const Ctx& C, int b, int h, int half, const bf16* HQ, const bf16* LOGF, bf16* HI  , float* SSQ) {
;     ...
;         for (int i = 0; i < 2; ++i) { const int p_ = tid + 512 * i; *(LAS v4u*)(L + O_RQ + ((p_ >> 4) * P128 + (p_ & 15) * 8) * 2) = rq[i]; }
; #pragma unroll
;         for (int i = 0; i < 2; ++i) { const int p_ = tid + 512 * i; *(LAS v4u*)(L + O_RL + ((p_ >> 4) * P128 + (p_ & 15) * 8) * 2) = rl[i]; }
;         { const unsigned vw[4] = {rv.x, rv.y, rv.z, rv.w};
; #pragma unroll
;           for (int j = 0; j < 4; ++j) { *(LAS bf16*)(L + O_VT + ((vt_d + 2 * j) * P64 + vt_t) * 2) = (bf16)(vw[j] & 0xffffu); *(LAS bf16*)(L + O_VT + ((vt_d + 2 * j + 1) * P64 + vt_t) * 2) = (bf16)(vw[j] >> 16); } }
;         if (c > 0) HG_STORE_O(c - 1);
.LBB0_708:
	s_cmp_lg_u32 s72, 0
	s_waitcnt vmcnt(4)
	ds_write_b128 v132, v[48:51]
	s_waitcnt vmcnt(3)
	ds_write_b128 v133, v[52:55]
	s_waitcnt vmcnt(2)
	ds_write_b128 v132, v[56:59] offset:17408
	s_waitcnt vmcnt(1)
	ds_write_b128 v133, v[60:63] offset:17408
	s_waitcnt vmcnt(0)
	ds_write_b16 v134, v64
	ds_write_b16_d16_hi v135, v64
	ds_write_b16 v136, v65
	ds_write_b16_d16_hi v137, v65
	ds_write_b16 v138, v66
	ds_write_b16_d16_hi v139, v66
	ds_write_b16 v140, v67
	ds_write_b16_d16_hi v141, v67
	s_cbranch_scc0 .LBB0_712
	v_add_u32_e32 v1, 0, v113
	v_add_u32_e32 v1, 0x1b200, v1
	ds_read_b128 v[6:9], v1
	s_lshl_b64 s[56:57], s[58:59], 6
	s_waitcnt lgkmcnt(0)
	v_and_b32_e32 v2, 0xffff0000, v6
	v_lshlrev_b32_e32 v1, 16, v6
	v_mul_f32_e32 v2, v2, v2
	v_lshlrev_b32_e32 v3, 16, v7
	v_fmac_f32_e32 v2, v1, v1
	v_and_b32_e32 v4, 0xffff0000, v7
	v_fmac_f32_e32 v2, v3, v3
	v_lshlrev_b32_e32 v5, 16, v8
	v_fmac_f32_e32 v2, v4, v4
	v_fmac_f32_e32 v2, v5, v5
	v_and_b32_e32 v1, 0xffff0000, v8
	v_fmac_f32_e32 v2, v1, v1
	v_lshlrev_b32_e32 v1, 16, v9
	v_fmac_f32_e32 v2, v1, v1
	v_and_b32_e32 v1, 0xffff0000, v9
	v_and_b32_e32 v3, 64, v110
	v_fmac_f32_e32 v2, v1, v1
	v_xor_b32_e32 v1, 1, v110
	v_add_u32_e32 v3, 64, v3
	v_cmp_lt_i32_e32 vcc, v1, v3
	s_nop 1
	v_cndmask_b32_e32 v1, v110, v1, vcc
	v_lshlrev_b32_e32 v1, 2, v1
	s_nop 1
	v_add_f32_dpp v1, v2, v2 quad_perm:[1,0,3,2] row_mask:0xf bank_mask:0xf
	v_xor_b32_e32 v2, 2, v110
	v_cmp_lt_i32_e32 vcc, v2, v3
	s_nop 1
	v_cndmask_b32_e32 v2, v110, v2, vcc
	v_lshlrev_b32_e32 v2, 2, v2
	s_nop 1
	v_add_f32_dpp v1, v1, v1 quad_perm:[2,3,0,1] row_mask:0xf bank_mask:0xf
	v_xor_b32_e32 v2, 4, v110
	v_cmp_lt_i32_e32 vcc, v2, v3
	s_nop 1
	v_cndmask_b32_e32 v2, v110, v2, vcc
	v_lshlrev_b32_e32 v2, 2, v2
	s_nop 1
	v_mov_b32_dpp v4, v1 row_half_mirror row_mask:0xf bank_mask:0xf
	v_lshl_add_u64 v[2:3], s[56:57], 0, v[72:73]
	v_lshlrev_b64 v[10:11], 12, v[2:3]
	v_lshl_add_u64 v[10:11], v[74:75], 0, v[10:11]
	global_store_dwordx4 v[10:11], v[6:9], off
	s_and_saveexec_b64 s[56:57], s[4:5]
	s_cbranch_execz .LBB0_711
	v_lshlrev_b64 v[2:3], 7, v[2:3]
	v_lshl_add_u64 v[2:3], s[70:71], 0, v[2:3]
	s_waitcnt lgkmcnt(0)
	v_add_f32_e32 v1, v1, v4
	global_store_dword v[2:3], v1, off

; __device__ __forceinline__ void scan_item(const Ctx& C, int b, int h, int half, const bf16* HQ, const bf16* LOGF, bf16* HI  , float* SSQ) {
;     ...
;     HG_STORE_O(SEQ / 64 - 1);
.LBB0_725:
	v_add_u32_e32 v1, 0, v113
	v_add_u32_e32 v1, 0x1b200, v1
	ds_read_b128 v[6:9], v1
	s_mov_b64 s[6:7], 0x7c0
	v_readlane_b32 s62, v232, 54
	v_readlane_b32 s63, v232, 55
	s_lshl_b32 s58, s1, 1
	s_waitcnt lgkmcnt(0)
	v_and_b32_e32 v2, 0xffff0000, v6
	v_lshlrev_b32_e32 v1, 16, v6
	v_mul_f32_e32 v2, v2, v2
	v_lshlrev_b32_e32 v3, 16, v7
	v_fmac_f32_e32 v2, v1, v1
	v_and_b32_e32 v4, 0xffff0000, v7
	v_fmac_f32_e32 v2, v3, v3
	v_lshlrev_b32_e32 v5, 16, v8
	v_fmac_f32_e32 v2, v4, v4
	v_fmac_f32_e32 v2, v5, v5
	v_and_b32_e32 v1, 0xffff0000, v8
	v_fmac_f32_e32 v2, v1, v1
	v_lshlrev_b32_e32 v1, 16, v9
	v_fmac_f32_e32 v2, v1, v1
	v_and_b32_e32 v1, 0xffff0000, v9
	v_and_b32_e32 v3, 64, v110
	v_fmac_f32_e32 v2, v1, v1
	v_xor_b32_e32 v1, 1, v110
	v_add_u32_e32 v3, 64, v3
	v_cmp_lt_i32_e32 vcc, v1, v3
	v_lshlrev_b32_e32 v12, 1, v68
	v_mov_b32_e32 v13, v0
	v_cndmask_b32_e32 v1, v110, v1, vcc
	v_lshlrev_b32_e32 v1, 2, v1
	s_nop 1
	v_add_f32_dpp v1, v2, v2 quad_perm:[1,0,3,2] row_mask:0xf bank_mask:0xf
	v_xor_b32_e32 v2, 2, v110
	v_cmp_lt_i32_e32 vcc, v2, v3
	s_nop 1
	v_cndmask_b32_e32 v2, v110, v2, vcc
	v_lshlrev_b32_e32 v2, 2, v2
	s_nop 1
	v_add_f32_dpp v1, v1, v1 quad_perm:[2,3,0,1] row_mask:0xf bank_mask:0xf
	v_xor_b32_e32 v2, 4, v110
	v_cmp_lt_i32_e32 vcc, v2, v3
	s_nop 1
	v_cndmask_b32_e32 v2, v110, v2, vcc
	v_lshlrev_b32_e32 v2, 2, v2
	s_nop 1
	v_mov_b32_dpp v4, v1 row_half_mirror row_mask:0xf bank_mask:0xf
	v_lshl_add_u64 v[2:3], v[70:71], 0, s[60:61]
	v_lshl_add_u64 v[2:3], v[2:3], 0, s[6:7]
	v_lshlrev_b64 v[10:11], 12, v[2:3]
	v_lshl_add_u64 v[10:11], s[62:63], 0, v[10:11]
	v_lshl_add_u64 v[10:11], v[10:11], 0, s[58:59]
	s_lshl_b32 s58, s80, 1
	v_lshl_add_u64 v[10:11], v[10:11], 0, s[58:59]
	v_lshl_add_u64 v[10:11], v[10:11], 0, v[12:13]
	global_store_dwordx4 v[10:11], v[6:9], off
	s_and_saveexec_b64 s[6:7], s[4:5]
	s_cbranch_execz .LBB0_702
	v_lshlrev_b64 v[2:3], 7, v[2:3]
	v_lshl_add_u64 v[2:3], s[82:83], 0, v[2:3]
	s_lshl_b32 s58, s76, 2
	v_lshl_add_u64 v[2:3], v[2:3], 0, s[58:59]
	s_lshl_b32 s58, s81, 2
	v_lshl_add_u64 v[2:3], v[2:3], 0, s[58:59]
	s_waitcnt lgkmcnt(0)
	v_add_f32_e32 v1, v1, v4
	global_store_dword v[2:3], v1, off
	s_branch .LBB0_702
